# v41 + V-fragment ds_read_tr also moved behind the exp/cvt fillers after PV1 (MFMA-first gap filling, all LDS reads late)
# speedup vs baseline: 1.0344x; 1.0283x over previous
.Latt_loop:
	s_add_i32 s13, s12, 1
	s_cmp_eq_u32 s12, 2
	s_cselect_b32 s12, 0, s13
	s_mul_i32 s15, s12, 0x4800
	s_mul_i32 s16, s12, 0x6000
	s_add_i32 s16, s16, 0xd800
	s_add_i32 s17, s14, 2
	s_min_u32 s17, s17, s11
	s_lshl_b32 s64, s17, 17
	s_add_u32 s18, s64, s83
	s_mov_b32 s19, 0
	s_add_i32 s14, s14, 1
	v_mov_b32_e32 v250, v251
	v_add3_u32 v251, s15, v236, v210
	v_mov_b32_e32 v252, v215
	v_add_u32_e32 v215, s16, v232
	s_waitcnt lgkmcnt(5)
	v_mfma_f32_32x32x16_bf16 v[98:113], v[238:241], v[134:137], 0
	v_exp_f32_e32 v66, v66
	v_exp_f32_e32 v67, v67
	v_exp_f32_e32 v68, v68
	ds_read_b128 v[238:241], v250 offset:4672
	v_mfma_f32_32x32x16_bf16 v[34:49], v[182:185], v[118:121], v[34:49]
	v_exp_f32_e32 v69, v69
	v_exp_f32_e32 v70, v70
	v_exp_f32_e32 v71, v71
	v_mfma_f32_32x32x16_bf16 v[50:65], v[186:189], v[118:121], v[50:65]
	v_exp_f32_e32 v72, v72
	v_exp_f32_e32 v73, v73
	v_cvt_pk_bf16_f32 v66, v66, v67
	v_cvt_pk_bf16_f32 v67, v68, v69
	ds_read_b64_tr_b16 v[182:183], v252 offset:3072
	ds_read_b64_tr_b16 v[184:185], v252 offset:4608
	ds_read_b64_tr_b16 v[186:187], v252 offset:3136
	ds_read_b64_tr_b16 v[188:189], v252 offset:4672
	v_mfma_f32_16x16x32_bf16 v[170:173], v[130:133], v[118:121], v[170:173]
	v_cvt_pk_bf16_f32 v68, v70, v71
	v_cvt_pk_bf16_f32 v69, v72, v73
	s_waitcnt vmcnt(0)
	v_add_u32_e32 v246, s15, v204
	v_add_u32_e32 v247, s16, v231
	ds_write_b128 v246, v[158:161]
	ds_write_b128 v246, v[162:165] offset:9216
	ds_write_b128 v247, v[150:153]
	ds_write_b128 v247, v[154:157] offset:12288
	s_add_u32 s18, s100, s64
	s_addc_u32 s19, s101, 0
	global_load_dwordx4 v[158:161], v248, s[18:19]
	global_load_dwordx4 v[162:165], v249, s[18:19]
	s_add_u32 s18, s18, 0x1040000
	s_addc_u32 s19, s19, 0
	global_load_dwordx4 v[150:153], v248, s[18:19]
	global_load_dwordx4 v[154:157], v249, s[18:19]
	s_waitcnt lgkmcnt(9)
	v_mfma_f32_32x32x16_bf16 v[98:113], v[242:245], v[138:141], v[98:113]
	v_exp_f32_e32 v82, v82
	v_exp_f32_e32 v83, v83
	v_exp_f32_e32 v84, v84
	ds_read_b128 v[242:245], v250 offset:4704
	v_mfma_f32_32x32x16_bf16 v[2:17], v[174:177], v[66:69], v[2:17]
	v_exp_f32_e32 v85, v85
	v_exp_f32_e32 v86, v86
	v_exp_f32_e32 v87, v87
	v_mfma_f32_32x32x16_bf16 v[18:33], v[178:181], v[66:69], v[18:33]
	v_exp_f32_e32 v88, v88
	v_exp_f32_e32 v89, v89
	v_cvt_pk_bf16_f32 v82, v82, v83
	v_cvt_pk_bf16_f32 v83, v84, v85
	v_mfma_f32_16x16x32_bf16 v[166:169], v[130:133], v[66:69], v[166:169]
	v_cvt_pk_bf16_f32 v84, v86, v87
	v_cvt_pk_bf16_f32 v85, v88, v89
	s_waitcnt lgkmcnt(9)
	v_mfma_f32_32x32x16_bf16 v[114:129], v[238:241], v[142:145], 0
	v_exp_f32_e32 v74, v74
	v_exp_f32_e32 v75, v75
	v_exp_f32_e32 v76, v76
	ds_read_b128 v[238:241], v250 offset:9216
	v_mfma_f32_32x32x16_bf16 v[34:49], v[174:177], v[82:85], v[34:49]
	v_exp_f32_e32 v77, v77
	v_exp_f32_e32 v78, v78
	v_exp_f32_e32 v79, v79
	v_mfma_f32_32x32x16_bf16 v[50:65], v[178:181], v[82:85], v[50:65]
	v_exp_f32_e32 v80, v80
	v_exp_f32_e32 v81, v81
	v_cvt_pk_bf16_f32 v70, v74, v75
	v_cvt_pk_bf16_f32 v71, v76, v77
	ds_read_b64_tr_b16 v[174:175], v252 offset:6144
	ds_read_b64_tr_b16 v[176:177], v252 offset:7680
	ds_read_b64_tr_b16 v[178:179], v252 offset:6208
	ds_read_b64_tr_b16 v[180:181], v252 offset:7744
	v_mfma_f32_16x16x32_bf16 v[170:173], v[130:133], v[82:85], v[170:173]
	v_cvt_pk_bf16_f32 v72, v78, v79
	v_cvt_pk_bf16_f32 v73, v80, v81
	s_waitcnt lgkmcnt(5)
	v_mfma_f32_32x32x16_bf16 v[114:129], v[242:245], v[146:149], v[114:129]
	v_exp_f32_e32 v90, v90
	v_exp_f32_e32 v91, v91
	v_exp_f32_e32 v92, v92
	ds_read_b128 v[242:245], v250 offset:9248
	v_mfma_f32_32x32x16_bf16 v[2:17], v[182:185], v[70:73], v[2:17]
	v_exp_f32_e32 v93, v93
	v_exp_f32_e32 v94, v94
	v_exp_f32_e32 v95, v95
	v_mfma_f32_32x32x16_bf16 v[18:33], v[186:189], v[70:73], v[18:33]
	v_exp_f32_e32 v96, v96
	v_exp_f32_e32 v97, v97
	v_cvt_pk_bf16_f32 v86, v90, v91
	v_cvt_pk_bf16_f32 v87, v92, v93
	v_mfma_f32_16x16x32_bf16 v[166:169], v[130:133], v[70:73], v[166:169]
	v_cvt_pk_bf16_f32 v88, v94, v95
	v_cvt_pk_bf16_f32 v89, v96, v97
	s_waitcnt lgkmcnt(5)
	v_mfma_f32_32x32x16_bf16 v[66:81], v[238:241], v[134:137], 0
	v_exp_f32_e32 v98, v98
	v_exp_f32_e32 v99, v99
	v_exp_f32_e32 v100, v100
	ds_read_b128 v[238:241], v250 offset:9280
	v_mfma_f32_32x32x16_bf16 v[34:49], v[182:185], v[86:89], v[34:49]
	v_exp_f32_e32 v101, v101
	v_exp_f32_e32 v102, v102
	v_exp_f32_e32 v103, v103
	v_mfma_f32_32x32x16_bf16 v[50:65], v[186:189], v[86:89], v[50:65]
	v_exp_f32_e32 v104, v104
	v_exp_f32_e32 v105, v105
	v_cvt_pk_bf16_f32 v98, v98, v99
	v_cvt_pk_bf16_f32 v99, v100, v101
	ds_read_b64_tr_b16 v[182:183], v252 offset:9216
	ds_read_b64_tr_b16 v[184:185], v252 offset:10752
	ds_read_b64_tr_b16 v[186:187], v252 offset:9280
	ds_read_b64_tr_b16 v[188:189], v252 offset:10816
	v_mfma_f32_16x16x32_bf16 v[170:173], v[130:133], v[86:89], v[170:173]
	v_cvt_pk_bf16_f32 v100, v102, v103
	v_cvt_pk_bf16_f32 v101, v104, v105
	s_waitcnt lgkmcnt(5)
	v_mfma_f32_32x32x16_bf16 v[66:81], v[242:245], v[138:141], v[66:81]
	v_exp_f32_e32 v114, v114
	v_exp_f32_e32 v115, v115
	v_exp_f32_e32 v116, v116
	ds_read_b128 v[242:245], v250 offset:9312
	v_mfma_f32_32x32x16_bf16 v[2:17], v[174:177], v[98:101], v[2:17]
	v_exp_f32_e32 v117, v117
	v_exp_f32_e32 v118, v118
	v_exp_f32_e32 v119, v119
	v_mfma_f32_32x32x16_bf16 v[18:33], v[178:181], v[98:101], v[18:33]
	v_exp_f32_e32 v120, v120
	v_exp_f32_e32 v121, v121
	v_cvt_pk_bf16_f32 v114, v114, v115
	v_cvt_pk_bf16_f32 v115, v116, v117
	v_mfma_f32_16x16x32_bf16 v[166:169], v[130:133], v[98:101], v[166:169]
	v_cvt_pk_bf16_f32 v116, v118, v119
	v_cvt_pk_bf16_f32 v117, v120, v121
	s_waitcnt lgkmcnt(5)
	v_mfma_f32_32x32x16_bf16 v[82:97], v[238:241], v[142:145], 0
	v_exp_f32_e32 v106, v106
	v_exp_f32_e32 v107, v107
	v_exp_f32_e32 v108, v108
	ds_read_b128 v[238:241], v250 offset:13824
	v_mfma_f32_32x32x16_bf16 v[34:49], v[174:177], v[114:117], v[34:49]
	v_exp_f32_e32 v109, v109
	v_exp_f32_e32 v110, v110
	v_exp_f32_e32 v111, v111
	v_mfma_f32_32x32x16_bf16 v[50:65], v[178:181], v[114:117], v[50:65]
	v_exp_f32_e32 v112, v112
	v_exp_f32_e32 v113, v113
	v_cvt_pk_bf16_f32 v102, v106, v107
	v_cvt_pk_bf16_f32 v103, v108, v109
	ds_read_b64_tr_b16 v[174:175], v252 offset:12288
	ds_read_b64_tr_b16 v[176:177], v252 offset:13824
	ds_read_b64_tr_b16 v[178:179], v252 offset:12352
	ds_read_b64_tr_b16 v[180:181], v252 offset:13888
	v_mfma_f32_16x16x32_bf16 v[170:173], v[130:133], v[114:117], v[170:173]
	v_cvt_pk_bf16_f32 v104, v110, v111
	v_cvt_pk_bf16_f32 v105, v112, v113
	s_waitcnt lgkmcnt(5)
	v_mfma_f32_32x32x16_bf16 v[82:97], v[242:245], v[146:149], v[82:97]
	v_exp_f32_e32 v122, v122
	v_exp_f32_e32 v123, v123
	v_exp_f32_e32 v124, v124
	ds_read_b128 v[242:245], v250 offset:13856
	v_mfma_f32_32x32x16_bf16 v[2:17], v[182:185], v[102:105], v[2:17]
	v_exp_f32_e32 v125, v125
	v_exp_f32_e32 v126, v126
	v_exp_f32_e32 v127, v127
	v_mfma_f32_32x32x16_bf16 v[18:33], v[186:189], v[102:105], v[18:33]
	v_exp_f32_e32 v128, v128
	v_exp_f32_e32 v129, v129
	v_cvt_pk_bf16_f32 v118, v122, v123
	v_cvt_pk_bf16_f32 v119, v124, v125
	v_mfma_f32_16x16x32_bf16 v[166:169], v[130:133], v[102:105], v[166:169]
	v_cvt_pk_bf16_f32 v120, v126, v127
	v_cvt_pk_bf16_f32 v121, v128, v129
	s_waitcnt lgkmcnt(5)
	v_mfma_f32_32x32x16_bf16 v[98:113], v[238:241], v[134:137], 0
	v_exp_f32_e32 v66, v66
	v_exp_f32_e32 v67, v67
	v_exp_f32_e32 v68, v68
	ds_read_b128 v[238:241], v250 offset:13888
	v_mfma_f32_32x32x16_bf16 v[34:49], v[182:185], v[118:121], v[34:49]
	v_exp_f32_e32 v69, v69
	v_exp_f32_e32 v70, v70
	v_exp_f32_e32 v71, v71
	v_mfma_f32_32x32x16_bf16 v[50:65], v[186:189], v[118:121], v[50:65]
	v_exp_f32_e32 v72, v72
	v_exp_f32_e32 v73, v73
	v_cvt_pk_bf16_f32 v66, v66, v67
	v_cvt_pk_bf16_f32 v67, v68, v69
	ds_read_b64_tr_b16 v[182:183], v252 offset:15360
	ds_read_b64_tr_b16 v[184:185], v252 offset:16896
	ds_read_b64_tr_b16 v[186:187], v252 offset:15424
	ds_read_b64_tr_b16 v[188:189], v252 offset:16960
	v_mfma_f32_16x16x32_bf16 v[170:173], v[130:133], v[118:121], v[170:173]
	v_cvt_pk_bf16_f32 v68, v70, v71
	v_cvt_pk_bf16_f32 v69, v72, v73
	s_waitcnt lgkmcnt(5)
	v_mfma_f32_32x32x16_bf16 v[98:113], v[242:245], v[138:141], v[98:113]
	v_exp_f32_e32 v82, v82
	v_exp_f32_e32 v83, v83
	v_exp_f32_e32 v84, v84
	ds_read_b128 v[242:245], v250 offset:13920
	v_mfma_f32_32x32x16_bf16 v[2:17], v[174:177], v[66:69], v[2:17]
	v_exp_f32_e32 v85, v85
	v_exp_f32_e32 v86, v86
	v_exp_f32_e32 v87, v87
	v_mfma_f32_32x32x16_bf16 v[18:33], v[178:181], v[66:69], v[18:33]
	v_exp_f32_e32 v88, v88
	v_exp_f32_e32 v89, v89
	v_cvt_pk_bf16_f32 v82, v82, v83
	v_cvt_pk_bf16_f32 v83, v84, v85
	v_mfma_f32_16x16x32_bf16 v[166:169], v[130:133], v[66:69], v[166:169]
	v_cvt_pk_bf16_f32 v84, v86, v87
	v_cvt_pk_bf16_f32 v85, v88, v89
	s_barrier
	s_waitcnt lgkmcnt(5)
	v_mfma_f32_32x32x16_bf16 v[114:129], v[238:241], v[142:145], 0
	v_exp_f32_e32 v74, v74
	v_exp_f32_e32 v75, v75
	v_exp_f32_e32 v76, v76
	ds_read_b128 v[238:241], v251
	v_mfma_f32_32x32x16_bf16 v[34:49], v[174:177], v[82:85], v[34:49]
	v_exp_f32_e32 v77, v77
	v_exp_f32_e32 v78, v78
	v_exp_f32_e32 v79, v79
	v_mfma_f32_32x32x16_bf16 v[50:65], v[178:181], v[82:85], v[50:65]
	v_exp_f32_e32 v80, v80
	v_exp_f32_e32 v81, v81
	v_cvt_pk_bf16_f32 v70, v74, v75
	v_cvt_pk_bf16_f32 v71, v76, v77
	ds_read_b64_tr_b16 v[174:175], v252 offset:18432
	ds_read_b64_tr_b16 v[176:177], v252 offset:19968
	ds_read_b64_tr_b16 v[178:179], v252 offset:18496
	ds_read_b64_tr_b16 v[180:181], v252 offset:20032
	v_mfma_f32_16x16x32_bf16 v[170:173], v[130:133], v[82:85], v[170:173]
	v_cvt_pk_bf16_f32 v72, v78, v79
	v_cvt_pk_bf16_f32 v73, v80, v81
	s_waitcnt lgkmcnt(5)
	v_mfma_f32_32x32x16_bf16 v[114:129], v[242:245], v[146:149], v[114:129]
	v_exp_f32_e32 v90, v90
	v_exp_f32_e32 v91, v91
	v_exp_f32_e32 v92, v92
	ds_read_b128 v[242:245], v251 offset:32
	v_mfma_f32_32x32x16_bf16 v[2:17], v[182:185], v[70:73], v[2:17]
	v_exp_f32_e32 v93, v93
	v_exp_f32_e32 v94, v94
	v_exp_f32_e32 v95, v95
	v_mfma_f32_32x32x16_bf16 v[18:33], v[186:189], v[70:73], v[18:33]
	v_exp_f32_e32 v96, v96
	v_exp_f32_e32 v97, v97
	v_cvt_pk_bf16_f32 v86, v90, v91
	v_cvt_pk_bf16_f32 v87, v92, v93
	v_mfma_f32_16x16x32_bf16 v[166:169], v[130:133], v[70:73], v[166:169]
	v_cvt_pk_bf16_f32 v88, v94, v95
	v_cvt_pk_bf16_f32 v89, v96, v97
	s_waitcnt lgkmcnt(5)
	v_mfma_f32_32x32x16_bf16 v[66:81], v[238:241], v[134:137], 0
	v_exp_f32_e32 v98, v98
	v_exp_f32_e32 v99, v99
	v_exp_f32_e32 v100, v100
	ds_read_b128 v[238:241], v251 offset:64
	v_mfma_f32_32x32x16_bf16 v[34:49], v[182:185], v[86:89], v[34:49]
	v_exp_f32_e32 v101, v101
	v_exp_f32_e32 v102, v102
	v_exp_f32_e32 v103, v103
	v_mfma_f32_32x32x16_bf16 v[50:65], v[186:189], v[86:89], v[50:65]
	v_exp_f32_e32 v104, v104
	v_exp_f32_e32 v105, v105
	v_cvt_pk_bf16_f32 v98, v98, v99
	v_cvt_pk_bf16_f32 v99, v100, v101
	ds_read_b64_tr_b16 v[182:183], v252 offset:21504
	ds_read_b64_tr_b16 v[184:185], v252 offset:23040
	ds_read_b64_tr_b16 v[186:187], v252 offset:21568
	ds_read_b64_tr_b16 v[188:189], v252 offset:23104
	v_mfma_f32_16x16x32_bf16 v[170:173], v[130:133], v[86:89], v[170:173]
	v_cvt_pk_bf16_f32 v100, v102, v103
	v_cvt_pk_bf16_f32 v101, v104, v105
	s_waitcnt lgkmcnt(5)
	v_mfma_f32_32x32x16_bf16 v[66:81], v[242:245], v[138:141], v[66:81]
	v_exp_f32_e32 v114, v114
	v_exp_f32_e32 v115, v115
	v_exp_f32_e32 v116, v116
	ds_read_b128 v[242:245], v251 offset:96
	v_mfma_f32_32x32x16_bf16 v[2:17], v[174:177], v[98:101], v[2:17]
	v_exp_f32_e32 v117, v117
	v_exp_f32_e32 v118, v118
	v_exp_f32_e32 v119, v119
	v_mfma_f32_32x32x16_bf16 v[18:33], v[178:181], v[98:101], v[18:33]
	v_exp_f32_e32 v120, v120
	v_exp_f32_e32 v121, v121
	v_cvt_pk_bf16_f32 v114, v114, v115
	v_cvt_pk_bf16_f32 v115, v116, v117
	v_mfma_f32_16x16x32_bf16 v[166:169], v[130:133], v[98:101], v[166:169]
	v_cvt_pk_bf16_f32 v116, v118, v119
	v_cvt_pk_bf16_f32 v117, v120, v121
	s_waitcnt lgkmcnt(5)
	v_mfma_f32_32x32x16_bf16 v[82:97], v[238:241], v[142:145], 0
	v_exp_f32_e32 v106, v106
	v_exp_f32_e32 v107, v107
	v_exp_f32_e32 v108, v108
	ds_read_b128 v[238:241], v251 offset:4608
	v_mfma_f32_32x32x16_bf16 v[34:49], v[174:177], v[114:117], v[34:49]
	v_exp_f32_e32 v109, v109
	v_exp_f32_e32 v110, v110
	v_exp_f32_e32 v111, v111
	v_mfma_f32_32x32x16_bf16 v[50:65], v[178:181], v[114:117], v[50:65]
	v_exp_f32_e32 v112, v112
	v_exp_f32_e32 v113, v113
	v_cvt_pk_bf16_f32 v102, v106, v107
	v_cvt_pk_bf16_f32 v103, v108, v109
	ds_read_b64_tr_b16 v[174:175], v215
	ds_read_b64_tr_b16 v[176:177], v215 offset:1536
	ds_read_b64_tr_b16 v[178:179], v215 offset:64
	ds_read_b64_tr_b16 v[180:181], v215 offset:1600
	v_mfma_f32_16x16x32_bf16 v[170:173], v[130:133], v[114:117], v[170:173]
	v_cvt_pk_bf16_f32 v104, v110, v111
	v_cvt_pk_bf16_f32 v105, v112, v113
	s_waitcnt lgkmcnt(5)
	v_mfma_f32_32x32x16_bf16 v[82:97], v[242:245], v[146:149], v[82:97]
	v_exp_f32_e32 v122, v122
	v_exp_f32_e32 v123, v123
	v_exp_f32_e32 v124, v124
	ds_read_b128 v[242:245], v251 offset:4640
	v_mfma_f32_32x32x16_bf16 v[2:17], v[182:185], v[102:105], v[2:17]
	v_exp_f32_e32 v125, v125
	v_exp_f32_e32 v126, v126
	v_exp_f32_e32 v127, v127
	v_mfma_f32_32x32x16_bf16 v[18:33], v[186:189], v[102:105], v[18:33]
	v_exp_f32_e32 v128, v128
	v_exp_f32_e32 v129, v129
	v_cvt_pk_bf16_f32 v118, v122, v123
	v_cvt_pk_bf16_f32 v119, v124, v125
	v_mfma_f32_16x16x32_bf16 v[166:169], v[130:133], v[102:105], v[166:169]
	v_cvt_pk_bf16_f32 v120, v126, v127
	v_cvt_pk_bf16_f32 v121, v128, v129
	s_cmp_lg_u32 s14, s10
	s_cbranch_scc1 .Latt_loop
	s_waitcnt lgkmcnt(0)
	s_nop 1
	v_mfma_f32_16x16x32_bf16 v[170:173], v[130:133], v[118:121], v[170:173]
	v_mfma_f32_32x32x16_bf16 v[34:49], v[182:185], v[118:121], v[34:49]
	v_mfma_f32_32x32x16_bf16 v[50:65], v[186:189], v[118:121], v[50:65]
	s_nop 11
	global_load_dwordx4 v[98:101], v[212:213], off offset:32
	global_load_dwordx4 v[102:105], v[212:213], off offset:64
	global_load_dwordx4 v[106:109], v[212:213], off offset:96
	global_load_dwordx4 v[110:113], v[212:213], off offset:128
	global_load_dwordx4 v[114:117], v[212:213], off offset:160
	global_load_dwordx4 v[122:125], v[212:213], off offset:192
	global_load_dwordx4 v[126:129], v[212:213], off offset:224
	ds_bpermute_b32 v66, v237, v166
	s_nop 3
	ds_bpermute_b32 v67, v237, v170
	s_lshl_b32 s64, s9, 1
	v_mov_b32_e32 v215, v191
	s_mov_b32 s2, 0xf226000
	s_waitcnt lgkmcnt(1)
	v_div_scale_f32 v68, s[10:11], v66, v66, 1.0
	v_rcp_f32_e32 v69, v68
	s_add_i32 s8, s8, 1
	s_cmp_eq_u32 s8, s7
	v_fma_f32 v70, -v68, v69, 1.0
	v_fmac_f32_e32 v69, v70, v69
	v_div_scale_f32 v70, vcc, 1.0, v66, 1.0
	v_mul_f32_e32 v71, v70, v69
	v_fma_f32 v72, -v68, v71, v70
	v_fmac_f32_e32 v71, v72, v69
	v_fma_f32 v68, -v68, v71, v70
	v_div_fmas_f32 v68, v68, v69, v71
	v_div_fixup_f32 v66, v68, v66, 1.0
	s_waitcnt lgkmcnt(0)
	v_div_scale_f32 v68, s[10:11], v67, v67, v230
	v_rcp_f32_e32 v69, v68
	s_mov_b64 s[10:11], 0xf226400
	v_fma_f32 v70, -v68, v69, 1.0
	v_fmac_f32_e32 v69, v70, v69
	v_div_scale_f32 v70, vcc, v230, v67, v230
	v_mul_f32_e32 v71, v70, v69
	v_fma_f32 v72, -v68, v71, v70
	v_fmac_f32_e32 v71, v72, v69
	v_fma_f32 v68, -v68, v71, v70
	v_div_fmas_f32 v68, v68, v69, v71
	v_div_fixup_f32 v68, v68, v67, v230
	v_pk_mul_f32 v[62:63], v[62:63], v[68:69] op_sel_hi:[1,0]
	v_pk_mul_f32 v[34:35], v[34:35], v[68:69] op_sel_hi:[1,0]
	v_pk_fma_f32 v[30:31], v[30:31], v[66:67], v[62:63] op_sel_hi:[1,0,1] neg_lo:[0,0,1] neg_hi:[0,0,1]
	v_pk_mul_f32 v[62:63], v[64:65], v[68:69] op_sel_hi:[1,0]
	v_pk_mul_f32 v[36:37], v[36:37], v[68:69] op_sel_hi:[1,0]
	v_pk_fma_f32 v[32:33], v[32:33], v[66:67], v[62:63] op_sel_hi:[1,0,1] neg_lo:[0,0,1] neg_hi:[0,0,1]
	v_lshlrev_b64 v[62:63], 11, v[216:217]
	v_lshl_add_u64 v[62:63], s[54:55], 0, v[62:63]
	v_lshl_add_u64 v[74:75], v[62:63], 0, s[64:65]
	global_load_dwordx4 v[62:65], v[212:213], off
	v_pk_fma_f32 v[34:35], v[2:3], v[66:67], v[34:35] op_sel_hi:[1,0,1] neg_lo:[0,0,1] neg_hi:[0,0,1]
	v_pk_fma_f32 v[4:5], v[4:5], v[66:67], v[36:37] op_sel_hi:[1,0,1] neg_lo:[0,0,1] neg_hi:[0,0,1]
	v_pk_mul_f32 v[76:77], v[34:35], v[34:35]
	v_pk_mul_f32 v[40:41], v[40:41], v[68:69] op_sel_hi:[1,0]
	v_pk_mul_f32 v[38:39], v[38:39], v[68:69] op_sel_hi:[1,0]
	v_pk_mul_f32 v[44:45], v[44:45], v[68:69] op_sel_hi:[1,0]
	v_pk_mul_f32 v[42:43], v[42:43], v[68:69] op_sel_hi:[1,0]
	v_pk_mul_f32 v[48:49], v[48:49], v[68:69] op_sel_hi:[1,0]
	v_pk_mul_f32 v[46:47], v[46:47], v[68:69] op_sel_hi:[1,0]
	v_pk_mul_f32 v[52:53], v[52:53], v[68:69] op_sel_hi:[1,0]
	v_pk_mul_f32 v[50:51], v[50:51], v[68:69] op_sel_hi:[1,0]
	v_pk_mul_f32 v[56:57], v[56:57], v[68:69] op_sel_hi:[1,0]
	v_pk_mul_f32 v[54:55], v[54:55], v[68:69] op_sel_hi:[1,0]
	v_pk_mul_f32 v[60:61], v[60:61], v[68:69] op_sel_hi:[1,0]
	v_pk_mul_f32 v[58:59], v[58:59], v[68:69] op_sel_hi:[1,0]
	v_pk_mul_f32 v[36:37], v[4:5], v[4:5]
	v_pk_fma_f32 v[8:9], v[8:9], v[66:67], v[40:41] op_sel_hi:[1,0,1] neg_lo:[0,0,1] neg_hi:[0,0,1]
	v_pk_fma_f32 v[38:39], v[6:7], v[66:67], v[38:39] op_sel_hi:[1,0,1] neg_lo:[0,0,1] neg_hi:[0,0,1]
	v_pk_fma_f32 v[12:13], v[12:13], v[66:67], v[44:45] op_sel_hi:[1,0,1] neg_lo:[0,0,1] neg_hi:[0,0,1]
	v_pk_fma_f32 v[10:11], v[10:11], v[66:67], v[42:43] op_sel_hi:[1,0,1] neg_lo:[0,0,1] neg_hi:[0,0,1]
	v_pk_fma_f32 v[16:17], v[16:17], v[66:67], v[48:49] op_sel_hi:[1,0,1] neg_lo:[0,0,1] neg_hi:[0,0,1]
	v_pk_fma_f32 v[14:15], v[14:15], v[66:67], v[46:47] op_sel_hi:[1,0,1] neg_lo:[0,0,1] neg_hi:[0,0,1]
	v_pk_fma_f32 v[20:21], v[20:21], v[66:67], v[52:53] op_sel_hi:[1,0,1] neg_lo:[0,0,1] neg_hi:[0,0,1]
	v_pk_fma_f32 v[18:19], v[18:19], v[66:67], v[50:51] op_sel_hi:[1,0,1] neg_lo:[0,0,1] neg_hi:[0,0,1]
	v_pk_fma_f32 v[24:25], v[24:25], v[66:67], v[56:57] op_sel_hi:[1,0,1] neg_lo:[0,0,1] neg_hi:[0,0,1]
	v_pk_fma_f32 v[22:23], v[22:23], v[66:67], v[54:55] op_sel_hi:[1,0,1] neg_lo:[0,0,1] neg_hi:[0,0,1]
	v_pk_fma_f32 v[28:29], v[28:29], v[66:67], v[60:61] op_sel_hi:[1,0,1] neg_lo:[0,0,1] neg_hi:[0,0,1]
	v_pk_fma_f32 v[26:27], v[26:27], v[66:67], v[58:59] op_sel_hi:[1,0,1] neg_lo:[0,0,1] neg_hi:[0,0,1]
	v_add_f32_e32 v66, v76, v77
	v_add_f32_e32 v36, v36, v66
	v_pk_mul_f32 v[6:7], v[38:39], v[38:39]
	v_add_f32_e32 v36, v37, v36
	v_add_f32_e32 v6, v6, v36
	v_pk_mul_f32 v[40:41], v[8:9], v[8:9]
	v_add_f32_e32 v6, v7, v6
	v_add_f32_e32 v6, v40, v6
	v_pk_mul_f32 v[42:43], v[10:11], v[10:11]
	v_add_f32_e32 v6, v41, v6
	v_add_f32_e32 v6, v42, v6
	v_pk_mul_f32 v[44:45], v[12:13], v[12:13]
	v_add_f32_e32 v6, v43, v6
	v_add_f32_e32 v6, v44, v6
	v_pk_mul_f32 v[46:47], v[14:15], v[14:15]
	v_add_f32_e32 v6, v45, v6
	v_add_f32_e32 v6, v46, v6
	v_pk_mul_f32 v[48:49], v[16:17], v[16:17]
	v_add_f32_e32 v6, v47, v6
	v_add_f32_e32 v6, v48, v6
	v_pk_mul_f32 v[50:51], v[18:19], v[18:19]
	v_add_f32_e32 v6, v49, v6
	v_add_f32_e32 v6, v50, v6
	v_pk_mul_f32 v[52:53], v[20:21], v[20:21]
	v_add_f32_e32 v6, v51, v6
	v_add_f32_e32 v6, v52, v6
	v_pk_mul_f32 v[54:55], v[22:23], v[22:23]
	v_add_f32_e32 v6, v53, v6
	v_add_f32_e32 v6, v54, v6
	v_pk_mul_f32 v[56:57], v[24:25], v[24:25]
	v_add_f32_e32 v6, v55, v6
	v_add_f32_e32 v6, v56, v6
	v_pk_mul_f32 v[58:59], v[26:27], v[26:27]
	v_add_f32_e32 v6, v57, v6
	v_add_f32_e32 v6, v58, v6
	v_pk_mul_f32 v[60:61], v[28:29], v[28:29]
	v_add_f32_e32 v6, v59, v6
	v_add_f32_e32 v6, v60, v6
	v_pk_mul_f32 v[70:71], v[30:31], v[30:31]
	v_add_f32_e32 v6, v61, v6
	v_add_f32_e32 v6, v70, v6
	v_pk_mul_f32 v[72:73], v[32:33], v[32:33]
	v_add_f32_e32 v6, v71, v6
	v_add_f32_e32 v6, v72, v6
	v_add_f32_e32 v6, v73, v6
	ds_bpermute_b32 v7, v229, v6
	v_lshl_add_u64 v[74:75], v[74:75], 0, v[214:215]
	v_lshl_add_u64 v[2:3], v[74:75], 0, s[10:11]
	s_waitcnt lgkmcnt(0)
	v_add_f32_e32 v6, v6, v7
	v_fmamk_f32 v6, v6, 0x3c800000, v192
	v_cmp_gt_f32_e32 vcc, s70, v6
	v_mul_f32_e32 v7, 0x4b800000, v6
	s_nop 0
	v_cndmask_b32_e32 v6, v6, v7, vcc
	v_rsq_f32_e32 v6, v6
	s_nop 0
	v_mul_f32_e32 v7, 0x45800000, v6
	v_cndmask_b32_e32 v6, v6, v7, vcc
	v_mul_f32_e32 v36, v233, v6
	v_pk_mul_f32 v[6:7], v[34:35], v[36:37] op_sel_hi:[1,0]
	v_pk_mul_f32 v[4:5], v[4:5], v[36:37] op_sel_hi:[1,0]
	s_waitcnt vmcnt(0)
	v_pk_mul_f32 v[6:7], v[62:63], v[6:7]
	v_pk_mul_f32 v[4:5], v[64:65], v[4:5]
	v_cvt_pk_bf16_f32 v6, v6, v7
	v_cvt_pk_bf16_f32 v7, v4, v5
	v_add_co_u32_e32 v4, vcc, s2, v74
	v_pk_mul_f32 v[34:35], v[38:39], v[36:37] op_sel_hi:[1,0]
	s_nop 0
	v_addc_co_u32_e32 v5, vcc, 0, v75, vcc
	global_store_dwordx2 v[4:5], v[6:7], off offset:1024
	v_pk_mul_f32 v[8:9], v[8:9], v[36:37] op_sel_hi:[1,0]
	v_mov_b64_e32 v[4:5], v[98:99]
	v_mov_b64_e32 v[6:7], v[100:101]
	v_pk_mul_f32 v[4:5], v[4:5], v[34:35]
	v_pk_mul_f32 v[6:7], v[6:7], v[8:9]
	v_cvt_pk_bf16_f32 v4, v4, v5
	v_cvt_pk_bf16_f32 v5, v6, v7
	global_store_dwordx2 v[2:3], v[4:5], off offset:16
	v_pk_mul_f32 v[8:9], v[10:11], v[36:37] op_sel_hi:[1,0]
	v_mov_b64_e32 v[4:5], v[102:103]
	v_mov_b64_e32 v[6:7], v[104:105]
	v_pk_mul_f32 v[4:5], v[4:5], v[8:9]
	v_pk_mul_f32 v[8:9], v[12:13], v[36:37] op_sel_hi:[1,0]
	v_cvt_pk_bf16_f32 v4, v4, v5
	v_pk_mul_f32 v[6:7], v[6:7], v[8:9]
	v_pk_mul_f32 v[8:9], v[14:15], v[36:37] op_sel_hi:[1,0]
	v_cvt_pk_bf16_f32 v5, v6, v7
	global_store_dwordx2 v[2:3], v[4:5], off offset:32
	v_mov_b64_e32 v[4:5], v[106:107]
	v_mov_b64_e32 v[6:7], v[108:109]
	v_pk_mul_f32 v[4:5], v[4:5], v[8:9]
	v_pk_mul_f32 v[8:9], v[16:17], v[36:37] op_sel_hi:[1,0]
	v_cvt_pk_bf16_f32 v4, v4, v5
	v_pk_mul_f32 v[6:7], v[6:7], v[8:9]
	v_pk_mul_f32 v[8:9], v[18:19], v[36:37] op_sel_hi:[1,0]
	v_cvt_pk_bf16_f32 v5, v6, v7
	global_store_dwordx2 v[2:3], v[4:5], off offset:48
	v_mov_b64_e32 v[4:5], v[110:111]
	v_mov_b64_e32 v[6:7], v[112:113]
	v_pk_mul_f32 v[4:5], v[4:5], v[8:9]
	v_pk_mul_f32 v[8:9], v[20:21], v[36:37] op_sel_hi:[1,0]
	v_cvt_pk_bf16_f32 v4, v4, v5
	v_pk_mul_f32 v[6:7], v[6:7], v[8:9]
	v_pk_mul_f32 v[8:9], v[22:23], v[36:37] op_sel_hi:[1,0]
	v_cvt_pk_bf16_f32 v5, v6, v7
	global_store_dwordx2 v[2:3], v[4:5], off offset:64
	v_mov_b64_e32 v[4:5], v[114:115]
	v_mov_b64_e32 v[6:7], v[116:117]
	v_pk_mul_f32 v[4:5], v[4:5], v[8:9]
	v_pk_mul_f32 v[8:9], v[24:25], v[36:37] op_sel_hi:[1,0]
	v_cvt_pk_bf16_f32 v4, v4, v5
	v_pk_mul_f32 v[6:7], v[6:7], v[8:9]
	v_pk_mul_f32 v[8:9], v[26:27], v[36:37] op_sel_hi:[1,0]
	v_cvt_pk_bf16_f32 v5, v6, v7
	global_store_dwordx2 v[2:3], v[4:5], off offset:80
	v_mov_b64_e32 v[4:5], v[122:123]
	v_mov_b64_e32 v[6:7], v[124:125]
	v_pk_mul_f32 v[4:5], v[4:5], v[8:9]
	v_pk_mul_f32 v[8:9], v[28:29], v[36:37] op_sel_hi:[1,0]
	v_cvt_pk_bf16_f32 v4, v4, v5
	v_pk_mul_f32 v[6:7], v[6:7], v[8:9]
	v_pk_mul_f32 v[8:9], v[30:31], v[36:37] op_sel_hi:[1,0]
	v_cvt_pk_bf16_f32 v5, v6, v7
	global_store_dwordx2 v[2:3], v[4:5], off offset:96
	v_mov_b64_e32 v[4:5], v[126:127]
	v_mov_b64_e32 v[6:7], v[128:129]
	v_pk_mul_f32 v[4:5], v[4:5], v[8:9]
	v_pk_mul_f32 v[8:9], v[32:33], v[36:37] op_sel_hi:[1,0]
	v_cvt_pk_bf16_f32 v4, v4, v5
	v_pk_mul_f32 v[6:7], v[6:7], v[8:9]
	s_nop 0
	v_cvt_pk_bf16_f32 v5, v6, v7
	global_store_dwordx2 v[2:3], v[4:5], off offset:112
	s_cbranch_scc0 .LBB0_745
